# cmp2_task (NSA compression MLP 2nd layer) ks loop software-pipelined: 14 loads of step ks+1 in flight during step ks instead of 6 dependent round trips per step; same per-element op order; dtype comme
# speedup vs baseline: 1.0039x; 1.0039x over previous
; DI float bf2f(bf16_t v) { return __uint_as_float(((unsigned)v) << 16); }
; DI f32x16 mfma32(bf16x8 a, bf16x8 b, f32x16 c) { return __builtin_amdgcn_mfma_f32_32x32x16_bf16(a, b, c, 0, 0, 0); }
; DI f32x16 zero16() { f32x16 z; for (int i = 0; i < 16; ++i) z[i] = 0.f; return z; }
; DI float gelu_tanh(float x) { const float u = 0.7978845608028654f * (x + 0.044715f * x * x * x); const float e = __expf(2.f * u); const float th = 1.f - 2.f * frcp(e + 1.f); return 0.5f * x * (1.f + th); }
; DI bf16x8 pack8(const float* p) { u32x4 o; o.x = pk2h(p[0], p[1]); o.y = pk2h(p[2], p[3]); o.z = pk2h(p[4], p[5]); o.w = pk2h(p[6], p[7]); return __builtin_bit_cast(bf16x8, o); }
; DI void cmp2_task(const Params& p, int e, int kv, int rt) {
;     ...
;   const bf16_t* SPL = (const bf16_t*)(p.ws + O_SPL) + (size_t)kv * 8 * 2048 * 256 + (size_t)row * 256 + g * 8;
;   const float* bias = (const float*)(p.ws + A_BIAS1) + (e * 2 + kv) * 256 + g * 8;
;   const bf16_t* W2 = (const bf16_t*)(p.ws + W_C2 + (size_t)(e * 2 + kv) * SZ_C2) + (size_t)lr * 256 + g * 8;
;   f32x16 acc[4];
; #pragma unroll
;   for (int i = 0; i < 4; ++i) acc[i] = zero16();
; #pragma unroll 2
;   for (int ks = 0; ks < 16; ++ks) {
;     f32x4 a0 = *(const f32x4*)(bias + ks * 16), a1 = *(const f32x4*)(bias + ks * 16 + 4);
; #pragma unroll
;     for (int sp = 0; sp < 8; ++sp) { const bf16x8 r8 = *(const bf16x8*)(SPL + (size_t)sp * 2048 * 256 + ks * 16);
; #pragma unroll
;       for (int i = 0; i < 4; ++i) { a0[i] += bf2f((bf16_t)r8[i]); a1[i] += bf2f((bf16_t)r8[4 + i]); } }
;     float hv[8];
; #pragma unroll
;     for (int i = 0; i < 4; ++i) { hv[i] = gelu_tanh(a0[i]); hv[4 + i] = gelu_tanh(a1[i]); }
;     const bf16x8 hb = pack8(hv);
; #pragma unroll
;     for (int dt = 0; dt < 4; ++dt) { const bf16x8 w = *(const bf16x8*)(W2 + (size_t)dt * 32 * 256 + ks * 16); acc[dt] = mfma32(w, hb, acc[dt]); }
;   }
.LBB0_302:
	s_nop 1
	s_mov_b32 s10, 8
	s_add_u32 s14, s18, 0x22080000
	s_addc_u32 s15, s19, 0
	global_load_dwordx4 v[80:83], v78, s[14:15]
	s_add_u32 s14, s18, 0x22080000
	s_addc_u32 s15, s19, 0
	global_load_dwordx4 v[84:87], v78, s[14:15] offset:16
	s_add_u32 s14, s18, 0x2a5e5000
	s_addc_u32 s15, s19, 0
	global_load_dwordx4 v[108:111], v74, s[14:15]
	s_add_u32 s14, s18, 0x2a6e5000
	s_addc_u32 s15, s19, 0
	global_load_dwordx4 v[112:115], v74, s[14:15]
	s_add_u32 s14, s18, 0x2a7e5000
	s_addc_u32 s15, s19, 0
	global_load_dwordx4 v[116:119], v74, s[14:15]
	s_add_u32 s14, s18, 0x2a8e5000
	s_addc_u32 s15, s19, 0
	global_load_dwordx4 v[120:123], v74, s[14:15]
	s_add_u32 s14, s18, 0x2a9e5000
	s_addc_u32 s15, s19, 0
	global_load_dwordx4 v[124:127], v74, s[14:15]
	s_add_u32 s14, s18, 0x2aae5000
	s_addc_u32 s15, s19, 0
	global_load_dwordx4 v[128:131], v74, s[14:15]
	s_add_u32 s14, s18, 0x2abe5000
	s_addc_u32 s15, s19, 0
	global_load_dwordx4 v[132:135], v74, s[14:15]
	s_add_u32 s14, s18, 0x2ace5000
	s_addc_u32 s15, s19, 0
	global_load_dwordx4 v[136:139], v74, s[14:15]
	s_add_u32 s14, s18, 0x8c00000
	s_addc_u32 s15, s19, 0
	global_load_dwordx4 v[140:143], v76, s[14:15]
	s_add_u32 s14, s18, 0x8c04000
	s_addc_u32 s15, s19, 0
	global_load_dwordx4 v[144:147], v76, s[14:15]
	s_add_u32 s14, s18, 0x8c08000
	s_addc_u32 s15, s19, 0
	global_load_dwordx4 v[148:151], v76, s[14:15]
	s_add_u32 s14, s18, 0x8c0c000
	s_addc_u32 s15, s19, 0
	global_load_dwordx4 v[152:155], v76, s[14:15]
.Lcmp2_ks:
	s_add_u32 s14, s18, 0x22080000
	s_addc_u32 s15, s19, 0
	global_load_dwordx4 v[88:91], v78, s[14:15] offset:64
	s_add_u32 s14, s18, 0x22080000
	s_addc_u32 s15, s19, 0
	global_load_dwordx4 v[92:95], v78, s[14:15] offset:80
	s_add_u32 s14, s18, 0x2a5e5000
	s_addc_u32 s15, s19, 0
	global_load_dwordx4 v[156:159], v74, s[14:15] offset:32
	s_add_u32 s14, s18, 0x2a6e5000
	s_addc_u32 s15, s19, 0
	global_load_dwordx4 v[160:163], v74, s[14:15] offset:32
	s_add_u32 s14, s18, 0x2a7e5000
	s_addc_u32 s15, s19, 0
	global_load_dwordx4 v[164:167], v74, s[14:15] offset:32
	s_add_u32 s14, s18, 0x2a8e5000
	s_addc_u32 s15, s19, 0
	global_load_dwordx4 v[168:171], v74, s[14:15] offset:32
	s_add_u32 s14, s18, 0x2a9e5000
	s_addc_u32 s15, s19, 0
	global_load_dwordx4 v[172:175], v74, s[14:15] offset:32
	s_add_u32 s14, s18, 0x2aae5000
	s_addc_u32 s15, s19, 0
	global_load_dwordx4 v[176:179], v74, s[14:15] offset:32
	s_add_u32 s14, s18, 0x2abe5000
	s_addc_u32 s15, s19, 0
	global_load_dwordx4 v[180:183], v74, s[14:15] offset:32
	s_add_u32 s14, s18, 0x2ace5000
	s_addc_u32 s15, s19, 0
	global_load_dwordx4 v[184:187], v74, s[14:15] offset:32
	s_add_u32 s14, s18, 0x8c00000
	s_addc_u32 s15, s19, 0
	global_load_dwordx4 v[200:203], v76, s[14:15] offset:32
	s_add_u32 s14, s18, 0x8c04000
	s_addc_u32 s15, s19, 0
	global_load_dwordx4 v[204:207], v76, s[14:15] offset:32
	s_add_u32 s14, s18, 0x8c08000
	s_addc_u32 s15, s19, 0
	global_load_dwordx4 v[208:211], v76, s[14:15] offset:32
	s_add_u32 s14, s18, 0x8c0c000
	s_addc_u32 s15, s19, 0
	global_load_dwordx4 v[212:215], v76, s[14:15] offset:32
	s_waitcnt vmcnt(14)
	v_lshlrev_b32_e32 v66, 16, v108
	v_and_b32_e32 v67, 0xffff0000, v108
	v_lshlrev_b32_e32 v68, 16, v109
	v_and_b32_e32 v69, 0xffff0000, v109
	v_lshlrev_b32_e32 v70, 16, v110
	v_and_b32_e32 v71, 0xffff0000, v110
	v_lshlrev_b32_e32 v72, 16, v111
	v_and_b32_e32 v73, 0xffff0000, v111
	v_pk_add_f32 v[80:81], v[80:81], v[66:67]
	v_pk_add_f32 v[82:83], v[82:83], v[68:69]
	v_pk_add_f32 v[84:85], v[84:85], v[70:71]
	v_pk_add_f32 v[86:87], v[86:87], v[72:73]
	v_lshlrev_b32_e32 v66, 16, v112
	v_and_b32_e32 v67, 0xffff0000, v112
	v_lshlrev_b32_e32 v68, 16, v113
	v_and_b32_e32 v69, 0xffff0000, v113
	v_lshlrev_b32_e32 v70, 16, v114
	v_and_b32_e32 v71, 0xffff0000, v114
	v_lshlrev_b32_e32 v72, 16, v115
	v_and_b32_e32 v73, 0xffff0000, v115
	v_pk_add_f32 v[80:81], v[80:81], v[66:67]
	v_pk_add_f32 v[82:83], v[82:83], v[68:69]
	v_pk_add_f32 v[84:85], v[84:85], v[70:71]
	v_pk_add_f32 v[86:87], v[86:87], v[72:73]
	v_lshlrev_b32_e32 v66, 16, v116
	v_and_b32_e32 v67, 0xffff0000, v116
	v_lshlrev_b32_e32 v68, 16, v117
	v_and_b32_e32 v69, 0xffff0000, v117
	v_lshlrev_b32_e32 v70, 16, v118
	v_and_b32_e32 v71, 0xffff0000, v118
	v_lshlrev_b32_e32 v72, 16, v119
	v_and_b32_e32 v73, 0xffff0000, v119
	v_pk_add_f32 v[80:81], v[80:81], v[66:67]
	v_pk_add_f32 v[82:83], v[82:83], v[68:69]
	v_pk_add_f32 v[84:85], v[84:85], v[70:71]
	v_pk_add_f32 v[86:87], v[86:87], v[72:73]
	v_lshlrev_b32_e32 v66, 16, v120
	v_and_b32_e32 v67, 0xffff0000, v120
	v_lshlrev_b32_e32 v68, 16, v121
	v_and_b32_e32 v69, 0xffff0000, v121
	v_lshlrev_b32_e32 v70, 16, v122
	v_and_b32_e32 v71, 0xffff0000, v122
	v_lshlrev_b32_e32 v72, 16, v123
	v_and_b32_e32 v73, 0xffff0000, v123
	v_pk_add_f32 v[80:81], v[80:81], v[66:67]
	v_pk_add_f32 v[82:83], v[82:83], v[68:69]
	v_pk_add_f32 v[84:85], v[84:85], v[70:71]
	v_pk_add_f32 v[86:87], v[86:87], v[72:73]
	v_lshlrev_b32_e32 v66, 16, v124
	v_and_b32_e32 v67, 0xffff0000, v124
	v_lshlrev_b32_e32 v68, 16, v125
	v_and_b32_e32 v69, 0xffff0000, v125
	v_lshlrev_b32_e32 v70, 16, v126
	v_and_b32_e32 v71, 0xffff0000, v126
	v_lshlrev_b32_e32 v72, 16, v127
	v_and_b32_e32 v73, 0xffff0000, v127
	v_pk_add_f32 v[80:81], v[80:81], v[66:67]
	v_pk_add_f32 v[82:83], v[82:83], v[68:69]
	v_pk_add_f32 v[84:85], v[84:85], v[70:71]
	v_pk_add_f32 v[86:87], v[86:87], v[72:73]
	v_lshlrev_b32_e32 v66, 16, v128
	v_and_b32_e32 v67, 0xffff0000, v128
	v_lshlrev_b32_e32 v68, 16, v129
	v_and_b32_e32 v69, 0xffff0000, v129
	v_lshlrev_b32_e32 v70, 16, v130
	v_and_b32_e32 v71, 0xffff0000, v130
	v_lshlrev_b32_e32 v72, 16, v131
	v_and_b32_e32 v73, 0xffff0000, v131
; DI float bf2f(bf16_t v) { return __uint_as_float(((unsigned)v) << 16); }
; DI f32x16 mfma32(bf16x8 a, bf16x8 b, f32x16 c) { return __builtin_amdgcn_mfma_f32_32x32x16_bf16(a, b, c, 0, 0, 0); }
; DI float gelu_tanh(float x) { const float u = 0.7978845608028654f * (x + 0.044715f * x * x * x); const float e = __expf(2.f * u); const float th = 1.f - 2.f * frcp(e + 1.f); return 0.5f * x * (1.f + th); }
; DI bf16x8 pack8(const float* p) { u32x4 o; o.x = pk2h(p[0], p[1]); o.y = pk2h(p[2], p[3]); o.z = pk2h(p[4], p[5]); o.w = pk2h(p[6], p[7]); return __builtin_bit_cast(bf16x8, o); }
; DI void cmp2_task(const Params& p, int e, int kv, int rt) {
;     ...
;     for (int sp = 0; sp < 8; ++sp) { const bf16x8 r8 = *(const bf16x8*)(SPL + (size_t)sp * 2048 * 256 + ks * 16);
; #pragma unroll
;       for (int i = 0; i < 4; ++i) { a0[i] += bf2f((bf16_t)r8[i]); a1[i] += bf2f((bf16_t)r8[4 + i]); } }
;     float hv[8];
; #pragma unroll
;     for (int i = 0; i < 4; ++i) { hv[i] = gelu_tanh(a0[i]); hv[4 + i] = gelu_tanh(a1[i]); }
;     const bf16x8 hb = pack8(hv);
; #pragma unroll
;     for (int dt = 0; dt < 4; ++dt) { const bf16x8 w = *(const bf16x8*)(W2 + (size_t)dt * 32 * 256 + ks * 16); acc[dt] = mfma32(w, hb, acc[dt]); }
;   }
	v_pk_add_f32 v[80:81], v[80:81], v[66:67]
	v_pk_add_f32 v[82:83], v[82:83], v[68:69]
	v_pk_add_f32 v[84:85], v[84:85], v[70:71]
	v_pk_add_f32 v[86:87], v[86:87], v[72:73]
	v_lshlrev_b32_e32 v66, 16, v132
	v_and_b32_e32 v67, 0xffff0000, v132
	v_lshlrev_b32_e32 v68, 16, v133
	v_and_b32_e32 v69, 0xffff0000, v133
	v_lshlrev_b32_e32 v70, 16, v134
	v_and_b32_e32 v71, 0xffff0000, v134
	v_lshlrev_b32_e32 v72, 16, v135
	v_and_b32_e32 v73, 0xffff0000, v135
	v_pk_add_f32 v[80:81], v[80:81], v[66:67]
	v_pk_add_f32 v[82:83], v[82:83], v[68:69]
	v_pk_add_f32 v[84:85], v[84:85], v[70:71]
	v_pk_add_f32 v[86:87], v[86:87], v[72:73]
	v_lshlrev_b32_e32 v66, 16, v136
	v_and_b32_e32 v67, 0xffff0000, v136
	v_lshlrev_b32_e32 v68, 16, v137
	v_and_b32_e32 v69, 0xffff0000, v137
	v_lshlrev_b32_e32 v70, 16, v138
	v_and_b32_e32 v71, 0xffff0000, v138
	v_lshlrev_b32_e32 v72, 16, v139
	v_and_b32_e32 v73, 0xffff0000, v139
	v_pk_add_f32 v[80:81], v[80:81], v[66:67]
	v_pk_add_f32 v[82:83], v[82:83], v[68:69]
	v_pk_add_f32 v[84:85], v[84:85], v[70:71]
	v_pk_add_f32 v[86:87], v[86:87], v[72:73]
	v_mul_f32_e32 v96, 0x3d372713, v80
	v_mul_f32_e32 v98, 0x3d372713, v82
	v_mul_f32_e32 v100, 0x3d372713, v84
	v_mul_f32_e32 v102, 0x3d372713, v86
	v_mul_f32_e32 v97, 0x3d372713, v81
	v_mul_f32_e32 v99, 0x3d372713, v83
	v_mul_f32_e32 v101, 0x3d372713, v85
	v_mul_f32_e32 v103, 0x3d372713, v87
	v_mul_f32_e32 v96, v80, v96
	v_mul_f32_e32 v98, v82, v98
	v_mul_f32_e32 v100, v84, v100
	v_mul_f32_e32 v102, v86, v102
	v_mul_f32_e32 v97, v81, v97
	v_mul_f32_e32 v99, v83, v99
	v_mul_f32_e32 v101, v85, v101
	v_mul_f32_e32 v103, v87, v103
	v_fma_f32 v96, v80, v96, v80
	v_fma_f32 v98, v82, v98, v82
	v_fma_f32 v100, v84, v100, v84
	v_fma_f32 v102, v86, v102, v86
	v_fma_f32 v97, v81, v97, v81
	v_fma_f32 v99, v83, v99, v83
	v_fma_f32 v101, v85, v101, v85
	v_fma_f32 v103, v87, v103, v87
	v_mul_f32_e32 v96, 0x3f4c422a, v96
	v_mul_f32_e32 v98, 0x3f4c422a, v98
	v_mul_f32_e32 v100, 0x3f4c422a, v100
	v_mul_f32_e32 v102, 0x3f4c422a, v102
	v_mul_f32_e32 v97, 0x3f4c422a, v97
	v_mul_f32_e32 v99, 0x3f4c422a, v99
	v_mul_f32_e32 v101, 0x3f4c422a, v101
	v_mul_f32_e32 v103, 0x3f4c422a, v103
	v_add_f32_e32 v96, v96, v96
	v_add_f32_e32 v98, v98, v98
	v_add_f32_e32 v100, v100, v100
	v_add_f32_e32 v102, v102, v102
	v_add_f32_e32 v97, v97, v97
	v_add_f32_e32 v99, v99, v99
	v_add_f32_e32 v101, v101, v101
	v_add_f32_e32 v103, v103, v103
	v_mul_f32_e32 v96, 0x3fb8aa3b, v96
	v_mul_f32_e32 v98, 0x3fb8aa3b, v98
	v_mul_f32_e32 v100, 0x3fb8aa3b, v100
	v_mul_f32_e32 v102, 0x3fb8aa3b, v102
	v_mul_f32_e32 v97, 0x3fb8aa3b, v97
	v_mul_f32_e32 v99, 0x3fb8aa3b, v99
	v_mul_f32_e32 v101, 0x3fb8aa3b, v101
	v_mul_f32_e32 v103, 0x3fb8aa3b, v103
	v_exp_f32_e32 v96, v96
	v_exp_f32_e32 v98, v98
	v_exp_f32_e32 v100, v100
	v_exp_f32_e32 v102, v102
	v_exp_f32_e32 v97, v97
	v_exp_f32_e32 v99, v99
	v_exp_f32_e32 v101, v101
	v_exp_f32_e32 v103, v103
	v_pk_mul_f32 v[80:81], v[80:81], 0.5 op_sel_hi:[1,0]
	v_pk_mul_f32 v[82:83], v[82:83], 0.5 op_sel_hi:[1,0]
	v_pk_mul_f32 v[84:85], v[84:85], 0.5 op_sel_hi:[1,0]
	v_pk_mul_f32 v[86:87], v[86:87], 0.5 op_sel_hi:[1,0]
	v_add_f32_e32 v96, 1.0, v96
	v_add_f32_e32 v98, 1.0, v98
	v_add_f32_e32 v100, 1.0, v100
	v_add_f32_e32 v102, 1.0, v102
	v_add_f32_e32 v97, 1.0, v97
	v_add_f32_e32 v99, 1.0, v99
	v_add_f32_e32 v101, 1.0, v101
	v_add_f32_e32 v103, 1.0, v103
	v_rcp_f32_e32 v96, v96
	v_rcp_f32_e32 v98, v98
	v_rcp_f32_e32 v100, v100
	v_rcp_f32_e32 v102, v102
	v_rcp_f32_e32 v97, v97
	v_rcp_f32_e32 v99, v99
	v_rcp_f32_e32 v101, v101
	v_rcp_f32_e32 v103, v103
	s_nop 0
	v_pk_fma_f32 v[96:97], v[96:97], 2.0, 1.0 op_sel_hi:[1,0,0] neg_lo:[1,0,0] neg_hi:[1,0,0]
	v_pk_fma_f32 v[98:99], v[98:99], 2.0, 1.0 op_sel_hi:[1,0,0] neg_lo:[1,0,0] neg_hi:[1,0,0]
	v_pk_fma_f32 v[100:101], v[100:101], 2.0, 1.0 op_sel_hi:[1,0,0] neg_lo:[1,0,0] neg_hi:[1,0,0]
	v_pk_fma_f32 v[102:103], v[102:103], 2.0, 1.0 op_sel_hi:[1,0,0] neg_lo:[1,0,0] neg_hi:[1,0,0]
	v_pk_add_f32 v[96:97], v[96:97], 1.0 op_sel_hi:[1,0]
	v_pk_add_f32 v[98:99], v[98:99], 1.0 op_sel_hi:[1,0]
	v_pk_add_f32 v[100:101], v[100:101], 1.0 op_sel_hi:[1,0]
	v_pk_add_f32 v[102:103], v[102:103], 1.0 op_sel_hi:[1,0]
	v_pk_mul_f32 v[80:81], v[80:81], v[96:97]
	v_pk_mul_f32 v[82:83], v[82:83], v[98:99]
	v_pk_mul_f32 v[84:85], v[84:85], v[100:101]
	v_pk_mul_f32 v[86:87], v[86:87], v[102:103]
	v_cvt_pk_bf16_f32 v80, v80, v81
	v_cvt_pk_bf16_f32 v81, v82, v83
	v_cvt_pk_bf16_f32 v82, v84, v85
	v_cvt_pk_bf16_f32 v83, v86, v87
	s_nop 1
	v_mfma_f32_32x32x16_bf16 v[50:65], v[140:143], v[80:83], v[50:65]
	v_mfma_f32_32x32x16_bf16 v[34:49], v[144:147], v[80:83], v[34:49]
	v_mfma_f32_32x32x16_bf16 v[18:33], v[148:151], v[80:83], v[18:33]
	v_mfma_f32_32x32x16_bf16 v[2:17], v[152:155], v[80:83], v[2:17]
	s_cmp_lg_u32 s10, 1
	s_cselect_b32 s11, 64, 0
	s_cselect_b32 s16, 0x80, 0
	v_add_u32_e32 v74, s11, v74
	v_add_u32_e32 v76, s11, v76
	v_add_u32_e32 v78, s16, v78
	s_add_u32 s14, s18, 0x22080000
	s_addc_u32 s15, s19, 0
	global_load_dwordx4 v[80:83], v78, s[14:15]
	s_add_u32 s14, s18, 0x22080000
	s_addc_u32 s15, s19, 0
	global_load_dwordx4 v[84:87], v78, s[14:15] offset:16
	s_add_u32 s14, s18, 0x2a5e5000
	s_addc_u32 s15, s19, 0
	global_load_dwordx4 v[108:111], v74, s[14:15]
	s_add_u32 s14, s18, 0x2a6e5000
	s_addc_u32 s15, s19, 0
	global_load_dwordx4 v[112:115], v74, s[14:15]
	s_add_u32 s14, s18, 0x2a7e5000
	s_addc_u32 s15, s19, 0
	global_load_dwordx4 v[116:119], v74, s[14:15]
	s_add_u32 s14, s18, 0x2a8e5000
	s_addc_u32 s15, s19, 0
	global_load_dwordx4 v[120:123], v74, s[14:15]
	s_add_u32 s14, s18, 0x2a9e5000
	s_addc_u32 s15, s19, 0
	global_load_dwordx4 v[124:127], v74, s[14:15]
	s_add_u32 s14, s18, 0x2aae5000
	s_addc_u32 s15, s19, 0
	global_load_dwordx4 v[128:131], v74, s[14:15]
	s_add_u32 s14, s18, 0x2abe5000
	s_addc_u32 s15, s19, 0
	global_load_dwordx4 v[132:135], v74, s[14:15]
	s_add_u32 s14, s18, 0x2ace5000
	s_addc_u32 s15, s19, 0
	global_load_dwordx4 v[136:139], v74, s[14:15]
	s_add_u32 s14, s18, 0x8c00000
	s_addc_u32 s15, s19, 0
	global_load_dwordx4 v[140:143], v76, s[14:15]
	s_add_u32 s14, s18, 0x8c04000
	s_addc_u32 s15, s19, 0
	global_load_dwordx4 v[144:147], v76, s[14:15]
	s_add_u32 s14, s18, 0x8c08000
	s_addc_u32 s15, s19, 0
	global_load_dwordx4 v[148:151], v76, s[14:15]
	s_add_u32 s14, s18, 0x8c0c000
	s_addc_u32 s15, s19, 0
	global_load_dwordx4 v[152:155], v76, s[14:15]
	s_waitcnt vmcnt(14)
; DI float bf2f(bf16_t v) { return __uint_as_float(((unsigned)v) << 16); }
; DI float gelu_tanh(float x) { const float u = 0.7978845608028654f * (x + 0.044715f * x * x * x); const float e = __expf(2.f * u); const float th = 1.f - 2.f * frcp(e + 1.f); return 0.5f * x * (1.f + th); }
; DI void cmp2_task(const Params& p, int e, int kv, int rt) {
;     ...
;     for (int sp = 0; sp < 8; ++sp) { const bf16x8 r8 = *(const bf16x8*)(SPL + (size_t)sp * 2048 * 256 + ks * 16);
; #pragma unroll
;       for (int i = 0; i < 4; ++i) { a0[i] += bf2f((bf16_t)r8[i]); a1[i] += bf2f((bf16_t)r8[4 + i]); } }
;     float hv[8];
; #pragma unroll
;     for (int i = 0; i < 4; ++i) { hv[i] = gelu_tanh(a0[i]); hv[4 + i] = gelu_tanh(a1[i]); }
	v_lshlrev_b32_e32 v66, 16, v156
	v_and_b32_e32 v67, 0xffff0000, v156
	v_lshlrev_b32_e32 v68, 16, v157
	v_and_b32_e32 v69, 0xffff0000, v157
	v_lshlrev_b32_e32 v70, 16, v158
	v_and_b32_e32 v71, 0xffff0000, v158
	v_lshlrev_b32_e32 v72, 16, v159
	v_and_b32_e32 v73, 0xffff0000, v159
	v_pk_add_f32 v[88:89], v[88:89], v[66:67]
	v_pk_add_f32 v[90:91], v[90:91], v[68:69]
	v_pk_add_f32 v[92:93], v[92:93], v[70:71]
	v_pk_add_f32 v[94:95], v[94:95], v[72:73]
	v_lshlrev_b32_e32 v66, 16, v160
	v_and_b32_e32 v67, 0xffff0000, v160
	v_lshlrev_b32_e32 v68, 16, v161
	v_and_b32_e32 v69, 0xffff0000, v161
	v_lshlrev_b32_e32 v70, 16, v162
	v_and_b32_e32 v71, 0xffff0000, v162
	v_lshlrev_b32_e32 v72, 16, v163
	v_and_b32_e32 v73, 0xffff0000, v163
	v_pk_add_f32 v[88:89], v[88:89], v[66:67]
	v_pk_add_f32 v[90:91], v[90:91], v[68:69]
	v_pk_add_f32 v[92:93], v[92:93], v[70:71]
	v_pk_add_f32 v[94:95], v[94:95], v[72:73]
	v_lshlrev_b32_e32 v66, 16, v164
	v_and_b32_e32 v67, 0xffff0000, v164
	v_lshlrev_b32_e32 v68, 16, v165
	v_and_b32_e32 v69, 0xffff0000, v165
	v_lshlrev_b32_e32 v70, 16, v166
	v_and_b32_e32 v71, 0xffff0000, v166
	v_lshlrev_b32_e32 v72, 16, v167
	v_and_b32_e32 v73, 0xffff0000, v167
	v_pk_add_f32 v[88:89], v[88:89], v[66:67]
	v_pk_add_f32 v[90:91], v[90:91], v[68:69]
	v_pk_add_f32 v[92:93], v[92:93], v[70:71]
	v_pk_add_f32 v[94:95], v[94:95], v[72:73]
	v_lshlrev_b32_e32 v66, 16, v168
	v_and_b32_e32 v67, 0xffff0000, v168
	v_lshlrev_b32_e32 v68, 16, v169
	v_and_b32_e32 v69, 0xffff0000, v169
	v_lshlrev_b32_e32 v70, 16, v170
	v_and_b32_e32 v71, 0xffff0000, v170
	v_lshlrev_b32_e32 v72, 16, v171
	v_and_b32_e32 v73, 0xffff0000, v171
	v_pk_add_f32 v[88:89], v[88:89], v[66:67]
	v_pk_add_f32 v[90:91], v[90:91], v[68:69]
	v_pk_add_f32 v[92:93], v[92:93], v[70:71]
	v_pk_add_f32 v[94:95], v[94:95], v[72:73]
	v_lshlrev_b32_e32 v66, 16, v172
	v_and_b32_e32 v67, 0xffff0000, v172
	v_lshlrev_b32_e32 v68, 16, v173
	v_and_b32_e32 v69, 0xffff0000, v173
	v_lshlrev_b32_e32 v70, 16, v174
	v_and_b32_e32 v71, 0xffff0000, v174
	v_lshlrev_b32_e32 v72, 16, v175
	v_and_b32_e32 v73, 0xffff0000, v175
	v_pk_add_f32 v[88:89], v[88:89], v[66:67]
	v_pk_add_f32 v[90:91], v[90:91], v[68:69]
	v_pk_add_f32 v[92:93], v[92:93], v[70:71]
	v_pk_add_f32 v[94:95], v[94:95], v[72:73]
	v_lshlrev_b32_e32 v66, 16, v176
	v_and_b32_e32 v67, 0xffff0000, v176
	v_lshlrev_b32_e32 v68, 16, v177
	v_and_b32_e32 v69, 0xffff0000, v177
	v_lshlrev_b32_e32 v70, 16, v178
	v_and_b32_e32 v71, 0xffff0000, v178
	v_lshlrev_b32_e32 v72, 16, v179
	v_and_b32_e32 v73, 0xffff0000, v179
	v_pk_add_f32 v[88:89], v[88:89], v[66:67]
	v_pk_add_f32 v[90:91], v[90:91], v[68:69]
	v_pk_add_f32 v[92:93], v[92:93], v[70:71]
	v_pk_add_f32 v[94:95], v[94:95], v[72:73]
	v_lshlrev_b32_e32 v66, 16, v180
	v_and_b32_e32 v67, 0xffff0000, v180
	v_lshlrev_b32_e32 v68, 16, v181
	v_and_b32_e32 v69, 0xffff0000, v181
	v_lshlrev_b32_e32 v70, 16, v182
	v_and_b32_e32 v71, 0xffff0000, v182
	v_lshlrev_b32_e32 v72, 16, v183
	v_and_b32_e32 v73, 0xffff0000, v183
	v_pk_add_f32 v[88:89], v[88:89], v[66:67]
	v_pk_add_f32 v[90:91], v[90:91], v[68:69]
	v_pk_add_f32 v[92:93], v[92:93], v[70:71]
	v_pk_add_f32 v[94:95], v[94:95], v[72:73]
	v_lshlrev_b32_e32 v66, 16, v184
	v_and_b32_e32 v67, 0xffff0000, v184
	v_lshlrev_b32_e32 v68, 16, v185
	v_and_b32_e32 v69, 0xffff0000, v185
	v_lshlrev_b32_e32 v70, 16, v186
	v_and_b32_e32 v71, 0xffff0000, v186
	v_lshlrev_b32_e32 v72, 16, v187
	v_and_b32_e32 v73, 0xffff0000, v187
	v_pk_add_f32 v[88:89], v[88:89], v[66:67]
	v_pk_add_f32 v[90:91], v[90:91], v[68:69]
	v_pk_add_f32 v[92:93], v[92:93], v[70:71]
	v_pk_add_f32 v[94:95], v[94:95], v[72:73]
	v_mul_f32_e32 v96, 0x3d372713, v88
	v_mul_f32_e32 v98, 0x3d372713, v90
	v_mul_f32_e32 v100, 0x3d372713, v92
	v_mul_f32_e32 v102, 0x3d372713, v94
	v_mul_f32_e32 v97, 0x3d372713, v89
	v_mul_f32_e32 v99, 0x3d372713, v91
	v_mul_f32_e32 v101, 0x3d372713, v93
	v_mul_f32_e32 v103, 0x3d372713, v95
	v_mul_f32_e32 v96, v88, v96
	v_mul_f32_e32 v98, v90, v98
	v_mul_f32_e32 v100, v92, v100
	v_mul_f32_e32 v102, v94, v102
	v_mul_f32_e32 v97, v89, v97
	v_mul_f32_e32 v99, v91, v99
	v_mul_f32_e32 v101, v93, v101
	v_mul_f32_e32 v103, v95, v103
	v_fma_f32 v96, v88, v96, v88
	v_fma_f32 v98, v90, v98, v90
	v_fma_f32 v100, v92, v100, v92
	v_fma_f32 v102, v94, v102, v94
	v_fma_f32 v97, v89, v97, v89
	v_fma_f32 v99, v91, v99, v91
	v_fma_f32 v101, v93, v101, v93
	v_fma_f32 v103, v95, v103, v95
	v_mul_f32_e32 v96, 0x3f4c422a, v96
	v_mul_f32_e32 v98, 0x3f4c422a, v98
	v_mul_f32_e32 v100, 0x3f4c422a, v100
	v_mul_f32_e32 v102, 0x3f4c422a, v102
	v_mul_f32_e32 v97, 0x3f4c422a, v97
	v_mul_f32_e32 v99, 0x3f4c422a, v99
	v_mul_f32_e32 v101, 0x3f4c422a, v101
	v_mul_f32_e32 v103, 0x3f4c422a, v103
	v_add_f32_e32 v96, v96, v96
	v_add_f32_e32 v98, v98, v98
	v_add_f32_e32 v100, v100, v100
	v_add_f32_e32 v102, v102, v102
	v_add_f32_e32 v97, v97, v97
	v_add_f32_e32 v99, v99, v99
	v_add_f32_e32 v101, v101, v101
	v_add_f32_e32 v103, v103, v103
	v_mul_f32_e32 v96, 0x3fb8aa3b, v96
	v_mul_f32_e32 v98, 0x3fb8aa3b, v98
	v_mul_f32_e32 v100, 0x3fb8aa3b, v100
	v_mul_f32_e32 v102, 0x3fb8aa3b, v102
	v_mul_f32_e32 v97, 0x3fb8aa3b, v97
	v_mul_f32_e32 v99, 0x3fb8aa3b, v99
	v_mul_f32_e32 v101, 0x3fb8aa3b, v101
	v_mul_f32_e32 v103, 0x3fb8aa3b, v103
	v_exp_f32_e32 v96, v96
	v_exp_f32_e32 v98, v98
	v_exp_f32_e32 v100, v100
	v_exp_f32_e32 v102, v102
	v_exp_f32_e32 v97, v97
	v_exp_f32_e32 v99, v99
	v_exp_f32_e32 v101, v101
	v_exp_f32_e32 v103, v103
	v_pk_mul_f32 v[88:89], v[88:89], 0.5 op_sel_hi:[1,0]
	v_pk_mul_f32 v[90:91], v[90:91], 0.5 op_sel_hi:[1,0]
	v_pk_mul_f32 v[92:93], v[92:93], 0.5 op_sel_hi:[1,0]
	v_pk_mul_f32 v[94:95], v[94:95], 0.5 op_sel_hi:[1,0]
; DI float bf2f(bf16_t v) { return __uint_as_float(((unsigned)v) << 16); }
; DI f32x16 mfma32(bf16x8 a, bf16x8 b, f32x16 c) { return __builtin_amdgcn_mfma_f32_32x32x16_bf16(a, b, c, 0, 0, 0); }
; DI float gelu_tanh(float x) { const float u = 0.7978845608028654f * (x + 0.044715f * x * x * x); const float e = __expf(2.f * u); const float th = 1.f - 2.f * frcp(e + 1.f); return 0.5f * x * (1.f + th); }
; DI bf16x8 pack8(const float* p) { u32x4 o; o.x = pk2h(p[0], p[1]); o.y = pk2h(p[2], p[3]); o.z = pk2h(p[4], p[5]); o.w = pk2h(p[6], p[7]); return __builtin_bit_cast(bf16x8, o); }
; DI void cmp2_task(const Params& p, int e, int kv, int rt) {
;     ...
;     for (int sp = 0; sp < 8; ++sp) { const bf16x8 r8 = *(const bf16x8*)(SPL + (size_t)sp * 2048 * 256 + ks * 16);
; #pragma unroll
;       for (int i = 0; i < 4; ++i) { a0[i] += bf2f((bf16_t)r8[i]); a1[i] += bf2f((bf16_t)r8[4 + i]); } }
;     float hv[8];
; #pragma unroll
;     for (int i = 0; i < 4; ++i) { hv[i] = gelu_tanh(a0[i]); hv[4 + i] = gelu_tanh(a1[i]); }
;     const bf16x8 hb = pack8(hv);
; #pragma unroll
;     for (int dt = 0; dt < 4; ++dt) { const bf16x8 w = *(const bf16x8*)(W2 + (size_t)dt * 32 * 256 + ks * 16); acc[dt] = mfma32(w, hb, acc[dt]); }
;   }
;   if (kv == 0) {
	v_add_f32_e32 v96, 1.0, v96
	v_add_f32_e32 v98, 1.0, v98
	v_add_f32_e32 v100, 1.0, v100
	v_add_f32_e32 v102, 1.0, v102
	v_add_f32_e32 v97, 1.0, v97
	v_add_f32_e32 v99, 1.0, v99
	v_add_f32_e32 v101, 1.0, v101
	v_add_f32_e32 v103, 1.0, v103
	v_rcp_f32_e32 v96, v96
	v_rcp_f32_e32 v98, v98
	v_rcp_f32_e32 v100, v100
	v_rcp_f32_e32 v102, v102
	v_rcp_f32_e32 v97, v97
	v_rcp_f32_e32 v99, v99
	v_rcp_f32_e32 v101, v101
	v_rcp_f32_e32 v103, v103
	s_nop 0
	v_pk_fma_f32 v[96:97], v[96:97], 2.0, 1.0 op_sel_hi:[1,0,0] neg_lo:[1,0,0] neg_hi:[1,0,0]
	v_pk_fma_f32 v[98:99], v[98:99], 2.0, 1.0 op_sel_hi:[1,0,0] neg_lo:[1,0,0] neg_hi:[1,0,0]
	v_pk_fma_f32 v[100:101], v[100:101], 2.0, 1.0 op_sel_hi:[1,0,0] neg_lo:[1,0,0] neg_hi:[1,0,0]
	v_pk_fma_f32 v[102:103], v[102:103], 2.0, 1.0 op_sel_hi:[1,0,0] neg_lo:[1,0,0] neg_hi:[1,0,0]
	v_pk_add_f32 v[96:97], v[96:97], 1.0 op_sel_hi:[1,0]
	v_pk_add_f32 v[98:99], v[98:99], 1.0 op_sel_hi:[1,0]
	v_pk_add_f32 v[100:101], v[100:101], 1.0 op_sel_hi:[1,0]
	v_pk_add_f32 v[102:103], v[102:103], 1.0 op_sel_hi:[1,0]
	v_pk_mul_f32 v[88:89], v[88:89], v[96:97]
	v_pk_mul_f32 v[90:91], v[90:91], v[98:99]
	v_pk_mul_f32 v[92:93], v[92:93], v[100:101]
	v_pk_mul_f32 v[94:95], v[94:95], v[102:103]
	v_cvt_pk_bf16_f32 v88, v88, v89
	v_cvt_pk_bf16_f32 v89, v90, v91
	v_cvt_pk_bf16_f32 v90, v92, v93
	v_cvt_pk_bf16_f32 v91, v94, v95
	s_nop 1
	v_mfma_f32_32x32x16_bf16 v[50:65], v[200:203], v[88:91], v[50:65]
	v_mfma_f32_32x32x16_bf16 v[34:49], v[204:207], v[88:91], v[34:49]
	v_mfma_f32_32x32x16_bf16 v[18:33], v[208:211], v[88:91], v[18:33]
	v_mfma_f32_32x32x16_bf16 v[2:17], v[212:215], v[88:91], v[2:17]
	s_add_i32 s10, s10, -1
	s_cmp_eq_u32 s10, 0
	s_cbranch_scc0 .Lcmp2_ks
	s_waitcnt vmcnt(0)
	v_and_b32_e32 v66, 63, v104
	v_and_b32_e32 v72, 1, v0
	v_cmp_lt_u32_e32 vcc, 63, v104
	s_and_saveexec_b64 s[10:11], vcc
	s_xor_b64 s[10:11], exec, s[10:11]
	s_cbranch_execz .LBB0_305
; DI bf16_t f2bf(float x) { return (bf16_t)(pk2(x, 0.f) & 0xffffu); }
; DI int crow(int i, int g) { return (i & 3) + 8 * (i >> 2) + 4 * g; }
; DI void cmp2_task(const Params& p, int e, int kv, int rt) {
;     ...
;     bf16_t* ob = (bf16_t*)(p.ws + O_VCMPT) + (size_t)(row >> 8) * 128 * 256 + (size_t)((row & 255) >> 5) * 4096 + (row & 31);
; #pragma unroll
;     for (int dt = 0; dt < 4; ++dt)
; #pragma unroll
;       for (int i = 0; i < 16; ++i) ob[(size_t)(dt * 32 + crow(i, g)) * 32] = f2bf(acc[dt][i]);
	v_lshlrev_b32_e32 v0, 13, v66
	v_and_b32_e32 v66, 0x70000, v0
	v_mov_b32_e32 v67, v1
	v_lshl_add_u64 v[66:67], s[2:3], 0, v[66:67]
	v_and_b32_e32 v68, 0xe000, v0
	v_mov_b32_e32 v69, v1
	v_lshl_add_u64 v[66:67], v[66:67], 0, v[68:69]
	v_lshlrev_b32_e32 v68, 1, v106
	v_lshl_add_u64 v[66:67], v[66:67], 0, v[68:69]
	v_lshlrev_b32_e32 v68, 8, v72
	v_cvt_pk_bf16_f32 v0, v50, s0
	v_lshl_add_u64 v[66:67], v[66:67], 0, v[68:69]
	global_store_short v[66:67], v0, off
	v_cvt_pk_bf16_f32 v0, v51, s0
	global_store_short v[66:67], v0, off offset:64
	v_cvt_pk_bf16_f32 v0, v52, s0
	global_store_short v[66:67], v0, off offset:128
	v_cvt_pk_bf16_f32 v0, v53, s0
	global_store_short v[66:67], v0, off offset:192
	v_cvt_pk_bf16_f32 v0, v54, s0
	global_store_short v[66:67], v0, off offset:512
	v_cvt_pk_bf16_f32 v0, v55, s0
	global_store_short v[66:67], v0, off offset:576
	v_cvt_pk_bf16_f32 v0, v56, s0
	global_store_short v[66:67], v0, off offset:640
	v_cvt_pk_bf16_f32 v0, v57, s0
	global_store_short v[66:67], v0, off offset:704
	v_cvt_pk_bf16_f32 v0, v58, s0
	global_store_short v[66:67], v0, off offset:1024
	v_cvt_pk_bf16_f32 v0, v59, s0
	global_store_short v[66:67], v0, off offset:1088
	v_cvt_pk_bf16_f32 v0, v60, s0
	global_store_short v[66:67], v0, off offset:1152
	v_cvt_pk_bf16_f32 v0, v61, s0
	global_store_short v[66:67], v0, off offset:1216
	v_cvt_pk_bf16_f32 v0, v62, s0
	global_store_short v[66:67], v0, off offset:1536
	v_cvt_pk_bf16_f32 v0, v63, s0
	global_store_short v[66:67], v0, off offset:1600
	v_cvt_pk_bf16_f32 v0, v64, s0
	global_store_short v[66:67], v0, off offset:1664
	v_cvt_pk_bf16_f32 v0, v65, s0
	global_store_short v[66:67], v0, off offset:1728
	v_cvt_pk_bf16_f32 v0, v34, s0
	global_store_short v[66:67], v0, off offset:2048
	v_cvt_pk_bf16_f32 v0, v35, s0
	global_store_short v[66:67], v0, off offset:2112
	v_cvt_pk_bf16_f32 v0, v36, s0
	global_store_short v[66:67], v0, off offset:2176
	v_cvt_pk_bf16_f32 v0, v37, s0
	global_store_short v[66:67], v0, off offset:2240
	v_cvt_pk_bf16_f32 v0, v38, s0
	global_store_short v[66:67], v0, off offset:2560
	v_cvt_pk_bf16_f32 v0, v39, s0
	global_store_short v[66:67], v0, off offset:2624
	v_cvt_pk_bf16_f32 v0, v40, s0
	global_store_short v[66:67], v0, off offset:2688
	v_cvt_pk_bf16_f32 v0, v41, s0
	global_store_short v[66:67], v0, off offset:2752
	v_cvt_pk_bf16_f32 v0, v42, s0
	global_store_short v[66:67], v0, off offset:3072
	v_cvt_pk_bf16_f32 v0, v43, s0
	global_store_short v[66:67], v0, off offset:3136
	v_cvt_pk_bf16_f32 v0, v44, s0
	global_store_short v[66:67], v0, off offset:3200
	v_cvt_pk_bf16_f32 v0, v45, s0
	global_store_short v[66:67], v0, off offset:3264
	v_cvt_pk_bf16_f32 v0, v46, s0
	global_store_short v[66:67], v0, off offset:3584
	v_cvt_pk_bf16_f32 v0, v47, s0
	global_store_short v[66:67], v0, off offset:3648
	v_cvt_pk_bf16_f32 v0, v48, s0
	global_store_short v[66:67], v0, off offset:3712
	v_cvt_pk_bf16_f32 v0, v49, s0
	s_movk_i32 s13, 0x1000
	global_store_short v[66:67], v0, off offset:3776
	v_add_co_u32_e32 v66, vcc, s13, v66
	v_cvt_pk_bf16_f32 v0, v18, s0
	s_nop 0
	v_addc_co_u32_e32 v67, vcc, 0, v67, vcc
	global_store_short v[66:67], v0, off
	v_cvt_pk_bf16_f32 v0, v19, s0
	global_store_short v[66:67], v0, off offset:64
	v_cvt_pk_bf16_f32 v0, v20, s0
	global_store_short v[66:67], v0, off offset:128
	v_cvt_pk_bf16_f32 v0, v21, s0
	global_store_short v[66:67], v0, off offset:192
	v_cvt_pk_bf16_f32 v0, v22, s0
	global_store_short v[66:67], v0, off offset:512
	v_cvt_pk_bf16_f32 v0, v23, s0
	global_store_short v[66:67], v0, off offset:576
	v_cvt_pk_bf16_f32 v0, v24, s0
	global_store_short v[66:67], v0, off offset:640
	v_cvt_pk_bf16_f32 v0, v25, s0
	global_store_short v[66:67], v0, off offset:704
	v_cvt_pk_bf16_f32 v0, v26, s0
	global_store_short v[66:67], v0, off offset:1024
	v_cvt_pk_bf16_f32 v0, v27, s0
	global_store_short v[66:67], v0, off offset:1088
	v_cvt_pk_bf16_f32 v0, v28, s0
	global_store_short v[66:67], v0, off offset:1152
	v_cvt_pk_bf16_f32 v0, v29, s0
	global_store_short v[66:67], v0, off offset:1216
	v_cvt_pk_bf16_f32 v0, v30, s0
	global_store_short v[66:67], v0, off offset:1536
	v_cvt_pk_bf16_f32 v0, v31, s0
	global_store_short v[66:67], v0, off offset:1600
	v_cvt_pk_bf16_f32 v0, v32, s0
	global_store_short v[66:67], v0, off offset:1664
	v_cvt_pk_bf16_f32 v0, v33, s0
	global_store_short v[66:67], v0, off offset:1728
	v_cvt_pk_bf16_f32 v0, v2, s0
	global_store_short v[66:67], v0, off offset:2048
	v_cvt_pk_bf16_f32 v0, v3, s0
	global_store_short v[66:67], v0, off offset:2112
	v_cvt_pk_bf16_f32 v0, v4, s0
	global_store_short v[66:67], v0, off offset:2176
	v_cvt_pk_bf16_f32 v0, v5, s0
	global_store_short v[66:67], v0, off offset:2240
	v_cvt_pk_bf16_f32 v0, v6, s0
	global_store_short v[66:67], v0, off offset:2560
	v_cvt_pk_bf16_f32 v0, v7, s0
	global_store_short v[66:67], v0, off offset:2624
	v_cvt_pk_bf16_f32 v0, v8, s0
	global_store_short v[66:67], v0, off offset:2688
	v_cvt_pk_bf16_f32 v0, v9, s0
	global_store_short v[66:67], v0, off offset:2752
	v_cvt_pk_bf16_f32 v0, v10, s0
	global_store_short v[66:67], v0, off offset:3072
	v_cvt_pk_bf16_f32 v0, v11, s0
	global_store_short v[66:67], v0, off offset:3136
	v_cvt_pk_bf16_f32 v0, v12, s0
	global_store_short v[66:67], v0, off offset:3200
	v_cvt_pk_bf16_f32 v0, v13, s0
	global_store_short v[66:67], v0, off offset:3264
	v_cvt_pk_bf16_f32 v0, v14, s0
	global_store_short v[66:67], v0, off offset:3584
	v_cvt_pk_bf16_f32 v0, v15, s0
	global_store_short v[66:67], v0, off offset:3648
	v_cvt_pk_bf16_f32 v0, v16, s0
	global_store_short v[66:67], v0, off offset:3712
	v_cvt_pk_bf16_f32 v0, v17, s0
	global_store_short v[66:67], v0, off offset:3776
